# attention loop v3: last four PV MFMAs of a tile deferred under the next tile's first LDS reads
# speedup vs baseline: 1.0288x; 1.0061x over previous
; #define MFMA32(a, b, c) __builtin_amdgcn_mfma_f32_32x32x16_bf16((a), (b), (c), 0, 0, 0)
; #define WAIT_BAR0() asm volatile("s_waitcnt vmcnt(0) lgkmcnt(0)\n\ts_barrier" ::: "memory")
; #define DMA_TILE(kt_, so_) do { glds16(kgp + (size_t)(kt_) * 64 * 128, dk0 + (so_)); glds16(kgp + (size_t)(kt_) * 64 * 128 + 32 * 128, dk0 + (so_) + 8192); \
;     glds16(vgp + (kt_) * 64, dk0 + (so_) + 16384); glds16(vgp + (size_t)64 * SEQ + (kt_) * 64, dk0 + (so_) + 24576); } while (0)
; #define SOFTMAX_PACK(S_, P_, l_) do { _Pragma("unroll") for (int e = 0; e < 16; ++e) { S_[e] = __builtin_amdgcn_exp2f(S_[e]); l_ += S_[e]; } \
;         _Pragma("unroll") for (int s = 0; s < 2; ++s) { u32x4 a_; _Pragma("unroll") for (int q = 0; q < 4; ++q) a_[q] = cvtpk(S_[8 * s + 2 * q], S_[8 * s + 2 * q + 1]); P_[s] = __builtin_bit_cast(bf16x8, a_); } } while (0)
; DI void attn_item(const Params& p, char* lds, int l, int bh, int jt, float lam, float outscale) {
;     ...
;   for (int kt = 0; kt < nkt; ++kt) {
;     WAIT_BAR0();
;     const unsigned so = (kt & 1) * 32768;
;     if (kt + 1 < nkt) DMA_TILE(kt + 1, 32768 - so);
;     if (kt <= my_last) {
;     ...
;       bf16x8 pa0[2], pa1[2];
;       f32x16 S0, S1;
; #pragma unroll
;       for (int e = 0; e < 16; ++e) { S0[e] = 0.f; S1[e] = 0.f; }
; #pragma unroll
;       for (int ks = 0; ks < 4; ++ks) {
;         S0 = MFMA32(KFRAG(0, 0, ks), QFRAG(0, ks), S0);
;         S1 = MFMA32(KFRAG(0, 1, ks), QFRAG(1, ks), S1);
;       }
;       SOFTMAX_PACK(S0, pa0, l0);
;       SOFTMAX_PACK(S1, pa1, l1);
; #pragma unroll
;       for (int e = 0; e < 16; ++e) { S0[e] = 0.f; S1[e] = 0.f; }
; #pragma unroll
;       for (int ks = 0; ks < 4; ++ks) {
;         S0 = MFMA32(KFRAG(1, 0, ks), QFRAG(0, ks), S0);
;         S1 = MFMA32(KFRAG(1, 1, ks), QFRAG(1, ks), S1);
; #pragma unroll
;         for (int dd = 0; dd < 2; ++dd) {
;           const int d = (ks & 1) * 2 + dd, s = ks >> 1;
;           const bf16x8 vf = VFRAG(0, d, s);
;           O0[d] = MFMA32(vf, pa0[s], O0[d]);
;           O1[d] = MFMA32(vf, pa1[s], O1[d]);
;         }
;       }
.LBB0_727:
	s_cmp_gt_i32 s35, s25
	s_cbranch_scc1 .Lattn_a_idle
	v_add_u32_e32 v203, s49, v252
	ds_read_b128 v[226:229], v251 offset:32768
	ds_read_b128 v[160:163], v203
	v_xor_b32_e32 v204, 0x20, v203
	ds_read_b128 v[230:233], v251 offset:40960
	ds_read_b128 v[164:167], v204
	v_xor_b32_e32 v205, 0x40, v203
	ds_read_b128 v[240:243], v251 offset:49152
	ds_read_b128 v[168:171], v205
	v_xor_b32_e32 v209, 0x60, v203
	ds_read_b128 v[192:195], v251 offset:57344
	ds_read_b128 v[172:175], v209
	v_xor_b32_e32 v235, 0x80, v203
	v_xor_b32_e32 v236, 0xa0, v203
	v_xor_b32_e32 v237, 0xc0, v203
	v_xor_b32_e32 v244, 0xe0, v203
	s_cmp_eq_u32 s35, 0
	s_cbranch_scc1 .Lattn_nodefer
	v_mfma_f32_32x32x16_bf16 v[96:111], v[210:213], v[180:183], v[96:111]
	v_mfma_f32_32x32x16_bf16 v[80:95], v[214:217], v[180:183], v[80:95]
	v_mfma_f32_32x32x16_bf16 v[48:63], v[218:221], v[180:183], v[48:63]
	v_mfma_f32_32x32x16_bf16 v[16:31], v[222:225], v[180:183], v[16:31]
.Lattn_nodefer:
	s_waitcnt lgkmcnt(6)
	v_mfma_f32_32x32x16_bf16 v[144:159], v[160:163], v[226:229], 0
	ds_read_b128 v[210:213], v251
	ds_read_b128 v[160:163], v235
	s_cmp_ge_i32 s27, s24
	s_cbranch_scc1 .Ldma_skip_1
	s_mov_b32 m0, s54
	s_nop 0
	global_load_lds_dwordx4 v208, s[50:51]
.Ldma_skip_1:
	s_waitcnt lgkmcnt(6)
	v_mfma_f32_32x32x16_bf16 v[144:159], v[164:167], v[230:233], v[144:159]
	ds_read_b128 v[214:217], v251 offset:8192
	ds_read_b128 v[164:167], v236
	s_cmp_ge_i32 s27, s24
	s_cbranch_scc1 .Ldma_skip_2
	s_add_u32 s50, s50, 0x2000
	s_addc_u32 s51, s51, 0
	s_add_i32 s54, s54, 0x2000
	s_mov_b32 m0, s54
	s_nop 0
	global_load_lds_dwordx4 v208, s[50:51]
.Ldma_skip_2:
	s_waitcnt lgkmcnt(6)
	v_mfma_f32_32x32x16_bf16 v[144:159], v[168:171], v[240:243], v[144:159]
	ds_read_b128 v[218:221], v251 offset:16384
	ds_read_b128 v[168:171], v237
	s_cmp_ge_i32 s27, s24
	s_cbranch_scc1 .Ldma_skip_3
	s_add_i32 s54, s54, 0x2000
	s_mov_b32 m0, s54
	s_nop 0
	global_load_lds_dwordx4 v202, s[52:53]
.Ldma_skip_3:
	s_waitcnt lgkmcnt(6)
	v_mfma_f32_32x32x16_bf16 v[144:159], v[172:175], v[192:195], v[144:159]
	ds_read_b128 v[222:225], v251 offset:24576
	ds_read_b128 v[172:175], v244
	s_cmp_ge_i32 s27, s24
	s_cbranch_scc1 .Ldma_skip_4
	s_add_u32 s52, s52, 0x200000
	s_addc_u32 s53, s53, 0
	s_add_i32 s54, s54, 0x2000
	s_mov_b32 m0, s54
	s_nop 0
	global_load_lds_dwordx4 v202, s[52:53]
.Ldma_skip_4:
	s_waitcnt lgkmcnt(6)
	v_mfma_f32_32x32x16_bf16 v[128:143], v[160:163], v[210:213], 0
	ds_read_b128 v[176:179], v203 offset:8192
	v_exp_f32_e32 v144, v144
	v_exp_f32_e32 v145, v145
	v_add_f32_e32 v207, v207, v144
	v_add_f32_e32 v207, v207, v145
	s_waitcnt lgkmcnt(5)
	v_mfma_f32_32x32x16_bf16 v[128:143], v[164:167], v[214:217], v[128:143]
	ds_read_b128 v[180:183], v204 offset:8192
	v_cvt_pk_bf16_f32 v144, v144, v145
	v_exp_f32_e32 v146, v146
	v_exp_f32_e32 v147, v147
	v_add_f32_e32 v207, v207, v146
	s_waitcnt lgkmcnt(4)
	v_mfma_f32_32x32x16_bf16 v[128:143], v[168:171], v[218:221], v[128:143]
	ds_read_b128 v[184:187], v205 offset:8192
	v_add_f32_e32 v207, v207, v147
	v_cvt_pk_bf16_f32 v145, v146, v147
	v_exp_f32_e32 v148, v148
	v_exp_f32_e32 v149, v149
	s_waitcnt lgkmcnt(3)
	v_mfma_f32_32x32x16_bf16 v[128:143], v[172:175], v[222:225], v[128:143]
	ds_read_b128 v[188:191], v209 offset:8192
	v_add_f32_e32 v207, v207, v148
	v_add_f32_e32 v207, v207, v149
	v_cvt_pk_bf16_f32 v146, v148, v149
	v_exp_f32_e32 v150, v150
	s_waitcnt lgkmcnt(3)
	v_mfma_f32_32x32x16_bf16 v[160:175], v[176:179], v[226:229], 0
	ds_read_b128 v[226:229], v235 offset:8192
	v_exp_f32_e32 v151, v151
	v_add_f32_e32 v207, v207, v150
	v_add_f32_e32 v207, v207, v151
	v_cvt_pk_bf16_f32 v147, v150, v151
	s_waitcnt lgkmcnt(3)
	v_mfma_f32_32x32x16_bf16 v[160:175], v[180:183], v[230:233], v[160:175]
	ds_read_b128 v[230:233], v236 offset:8192
	v_exp_f32_e32 v128, v128
	v_exp_f32_e32 v129, v129
	v_add_f32_e32 v206, v206, v128
	v_add_f32_e32 v206, v206, v129
	s_waitcnt lgkmcnt(3)
	v_mfma_f32_32x32x16_bf16 v[160:175], v[184:187], v[240:243], v[160:175]
	ds_read_b128 v[240:243], v237 offset:8192
	v_cvt_pk_bf16_f32 v128, v128, v129
	v_exp_f32_e32 v130, v130
	v_exp_f32_e32 v131, v131
	v_add_f32_e32 v206, v206, v130
	s_waitcnt lgkmcnt(3)
	v_mfma_f32_32x32x16_bf16 v[160:175], v[188:191], v[192:195], v[160:175]
	ds_read_b128 v[192:195], v244 offset:8192
	v_add_f32_e32 v206, v206, v131
	v_cvt_pk_bf16_f32 v129, v130, v131
	v_exp_f32_e32 v132, v132
	v_exp_f32_e32 v133, v133
	v_add_u32_e32 v203, s49, v253
	v_xor_b32_e32 v204, 0x20, v203
	v_xor_b32_e32 v205, 0x40, v203
	v_xor_b32_e32 v209, 0x60, v203
	s_waitcnt lgkmcnt(3)
	v_mfma_f32_32x32x16_bf16 v[176:191], v[226:229], v[210:213], 0
	ds_read_b128 v[226:229], v203 offset:16384
	v_add_f32_e32 v206, v206, v132
	v_add_f32_e32 v206, v206, v133
	v_cvt_pk_bf16_f32 v130, v132, v133
	v_exp_f32_e32 v134, v134
	s_waitcnt lgkmcnt(3)
	v_mfma_f32_32x32x16_bf16 v[176:191], v[230:233], v[214:217], v[176:191]
	ds_read_b128 v[230:233], v203 offset:20480
	v_exp_f32_e32 v135, v135
	v_add_f32_e32 v206, v206, v134
	v_add_f32_e32 v206, v206, v135
	v_cvt_pk_bf16_f32 v131, v134, v135
	s_waitcnt lgkmcnt(3)
	v_mfma_f32_32x32x16_bf16 v[176:191], v[240:243], v[218:221], v[176:191]
	ds_read_b128 v[240:243], v203 offset:24576
	v_exp_f32_e32 v152, v152
	v_exp_f32_e32 v153, v153
	v_add_f32_e32 v207, v207, v152
	v_add_f32_e32 v207, v207, v153
	s_waitcnt lgkmcnt(3)
	v_mfma_f32_32x32x16_bf16 v[176:191], v[192:195], v[222:225], v[176:191]
	ds_read_b128 v[192:195], v203 offset:28672
	v_cvt_pk_bf16_f32 v148, v152, v153
	v_exp_f32_e32 v154, v154
	v_exp_f32_e32 v155, v155
	v_add_f32_e32 v207, v207, v154
	s_waitcnt lgkmcnt(3)
; #define MFMA32(a, b, c) __builtin_amdgcn_mfma_f32_32x32x16_bf16((a), (b), (c), 0, 0, 0)
; #define SOFTMAX_PACK(S_, P_, l_) do { _Pragma("unroll") for (int e = 0; e < 16; ++e) { S_[e] = __builtin_amdgcn_exp2f(S_[e]); l_ += S_[e]; } \
;         _Pragma("unroll") for (int s = 0; s < 2; ++s) { u32x4 a_; _Pragma("unroll") for (int q = 0; q < 4; ++q) a_[q] = cvtpk(S_[8 * s + 2 * q], S_[8 * s + 2 * q + 1]); P_[s] = __builtin_bit_cast(bf16x8, a_); } } while (0)
; DI void attn_item(const Params& p, char* lds, int l, int bh, int jt, float lam, float outscale) {
;     ...
;       SOFTMAX_PACK(S0, pa0, l0);
;       SOFTMAX_PACK(S1, pa1, l1);
; #pragma unroll
;       for (int e = 0; e < 16; ++e) { S0[e] = 0.f; S1[e] = 0.f; }
; #pragma unroll
;       for (int ks = 0; ks < 4; ++ks) {
;         S0 = MFMA32(KFRAG(1, 0, ks), QFRAG(0, ks), S0);
;         S1 = MFMA32(KFRAG(1, 1, ks), QFRAG(1, ks), S1);
; #pragma unroll
;         for (int dd = 0; dd < 2; ++dd) {
;           const int d = (ks & 1) * 2 + dd, s = ks >> 1;
;           const bf16x8 vf = VFRAG(0, d, s);
;           O0[d] = MFMA32(vf, pa0[s], O0[d]);
;           O1[d] = MFMA32(vf, pa1[s], O1[d]);
;         }
;       }
;       bf16x8 pc0[2], pc1[2];
;       SOFTMAX_PACK(S0, pc0, l0);
;       SOFTMAX_PACK(S1, pc1, l1);
; #pragma unroll
;       for (int s = 0; s < 2; ++s) {
; #pragma unroll
;         for (int d = 0; d < 4; ++d) {
;           const bf16x8 vf = VFRAG(1, d, s);
;           O0[d] = MFMA32(vf, pc0[s], O0[d]);
;           O1[d] = MFMA32(vf, pc1[s], O1[d]);
;         }
;       }
	v_mfma_f32_32x32x16_bf16 v[112:127], v[226:229], v[144:147], v[112:127]
	ds_read_b128 v[210:213], v204 offset:16384
	v_add_f32_e32 v207, v207, v155
	v_cvt_pk_bf16_f32 v149, v154, v155
	v_exp_f32_e32 v156, v156
	v_exp_f32_e32 v157, v157
	s_waitcnt lgkmcnt(3)
	v_mfma_f32_32x32x16_bf16 v[64:79], v[230:233], v[144:147], v[64:79]
	ds_read_b128 v[214:217], v204 offset:20480
	v_add_f32_e32 v207, v207, v156
	v_add_f32_e32 v207, v207, v157
	v_cvt_pk_bf16_f32 v150, v156, v157
	v_exp_f32_e32 v158, v158
	s_waitcnt lgkmcnt(3)
	v_mfma_f32_32x32x16_bf16 v[32:47], v[240:243], v[144:147], v[32:47]
	ds_read_b128 v[218:221], v204 offset:24576
	v_exp_f32_e32 v159, v159
	v_add_f32_e32 v207, v207, v158
	v_add_f32_e32 v207, v207, v159
	v_cvt_pk_bf16_f32 v151, v158, v159
	s_waitcnt lgkmcnt(3)
	v_mfma_f32_32x32x16_bf16 v[0:15], v[192:195], v[144:147], v[0:15]
	ds_read_b128 v[222:225], v204 offset:28672
	v_exp_f32_e32 v136, v136
	v_exp_f32_e32 v137, v137
	v_add_f32_e32 v206, v206, v136
	v_add_f32_e32 v206, v206, v137
	v_mfma_f32_32x32x16_bf16 v[96:111], v[226:229], v[128:131], v[96:111]
	v_cvt_pk_bf16_f32 v132, v136, v137
	v_exp_f32_e32 v138, v138
	v_exp_f32_e32 v139, v139
	v_add_f32_e32 v206, v206, v138
	v_mfma_f32_32x32x16_bf16 v[80:95], v[230:233], v[128:131], v[80:95]
	v_add_f32_e32 v206, v206, v139
	v_cvt_pk_bf16_f32 v133, v138, v139
	v_exp_f32_e32 v140, v140
	v_exp_f32_e32 v141, v141
	v_mfma_f32_32x32x16_bf16 v[48:63], v[240:243], v[128:131], v[48:63]
	v_add_f32_e32 v206, v206, v140
	v_add_f32_e32 v206, v206, v141
	v_cvt_pk_bf16_f32 v134, v140, v141
	v_exp_f32_e32 v142, v142
	v_mfma_f32_32x32x16_bf16 v[16:31], v[192:195], v[128:131], v[16:31]
	v_exp_f32_e32 v143, v143
	v_add_f32_e32 v206, v206, v142
	v_add_f32_e32 v206, v206, v143
	v_cvt_pk_bf16_f32 v135, v142, v143
	s_waitcnt lgkmcnt(3)
	v_mfma_f32_32x32x16_bf16 v[112:127], v[210:213], v[148:151], v[112:127]
	ds_read_b128 v[226:229], v205 offset:16384
	v_exp_f32_e32 v160, v160
	v_exp_f32_e32 v161, v161
	v_add_f32_e32 v207, v207, v160
	v_add_f32_e32 v207, v207, v161
	s_waitcnt lgkmcnt(3)
	v_mfma_f32_32x32x16_bf16 v[64:79], v[214:217], v[148:151], v[64:79]
	ds_read_b128 v[230:233], v205 offset:20480
	v_cvt_pk_bf16_f32 v160, v160, v161
	v_exp_f32_e32 v162, v162
	v_exp_f32_e32 v163, v163
	v_add_f32_e32 v207, v207, v162
	s_waitcnt lgkmcnt(3)
	v_mfma_f32_32x32x16_bf16 v[32:47], v[218:221], v[148:151], v[32:47]
	ds_read_b128 v[240:243], v205 offset:24576
	v_add_f32_e32 v207, v207, v163
	v_cvt_pk_bf16_f32 v161, v162, v163
	v_exp_f32_e32 v164, v164
	v_exp_f32_e32 v165, v165
	s_waitcnt lgkmcnt(3)
	v_mfma_f32_32x32x16_bf16 v[0:15], v[222:225], v[148:151], v[0:15]
	ds_read_b128 v[192:195], v205 offset:28672
	v_add_f32_e32 v207, v207, v164
	v_add_f32_e32 v207, v207, v165
	v_cvt_pk_bf16_f32 v162, v164, v165
	v_exp_f32_e32 v166, v166
	v_mfma_f32_32x32x16_bf16 v[96:111], v[210:213], v[132:135], v[96:111]
	v_exp_f32_e32 v167, v167
	v_add_f32_e32 v207, v207, v166
	v_add_f32_e32 v207, v207, v167
	v_cvt_pk_bf16_f32 v163, v166, v167
	v_mfma_f32_32x32x16_bf16 v[80:95], v[214:217], v[132:135], v[80:95]
	v_exp_f32_e32 v176, v176
	v_exp_f32_e32 v177, v177
	v_add_f32_e32 v206, v206, v176
	v_add_f32_e32 v206, v206, v177
	v_mfma_f32_32x32x16_bf16 v[48:63], v[218:221], v[132:135], v[48:63]
	v_cvt_pk_bf16_f32 v176, v176, v177
	v_exp_f32_e32 v178, v178
	v_exp_f32_e32 v179, v179
	v_add_f32_e32 v206, v206, v178
	v_mfma_f32_32x32x16_bf16 v[16:31], v[222:225], v[132:135], v[16:31]
	v_add_f32_e32 v206, v206, v179
	v_cvt_pk_bf16_f32 v177, v178, v179
	v_exp_f32_e32 v180, v180
	v_exp_f32_e32 v181, v181
	s_waitcnt lgkmcnt(3)
	v_mfma_f32_32x32x16_bf16 v[112:127], v[226:229], v[160:163], v[112:127]
	ds_read_b128 v[210:213], v209 offset:16384
	v_add_f32_e32 v206, v206, v180
	v_add_f32_e32 v206, v206, v181
	v_cvt_pk_bf16_f32 v178, v180, v181
	v_exp_f32_e32 v182, v182
	s_waitcnt lgkmcnt(3)
	v_mfma_f32_32x32x16_bf16 v[64:79], v[230:233], v[160:163], v[64:79]
	ds_read_b128 v[214:217], v209 offset:20480
	v_exp_f32_e32 v183, v183
	v_add_f32_e32 v206, v206, v182
	v_add_f32_e32 v206, v206, v183
	v_cvt_pk_bf16_f32 v179, v182, v183
	s_waitcnt lgkmcnt(3)
	v_mfma_f32_32x32x16_bf16 v[32:47], v[240:243], v[160:163], v[32:47]
	ds_read_b128 v[218:221], v209 offset:24576
	v_exp_f32_e32 v168, v168
	v_exp_f32_e32 v169, v169
	v_add_f32_e32 v207, v207, v168
	v_add_f32_e32 v207, v207, v169
	s_waitcnt lgkmcnt(3)
	v_mfma_f32_32x32x16_bf16 v[0:15], v[192:195], v[160:163], v[0:15]
	ds_read_b128 v[222:225], v209 offset:28672
	v_cvt_pk_bf16_f32 v164, v168, v169
	v_exp_f32_e32 v170, v170
	v_exp_f32_e32 v171, v171
	v_add_f32_e32 v207, v207, v170
	v_mfma_f32_32x32x16_bf16 v[96:111], v[226:229], v[176:179], v[96:111]
	v_add_f32_e32 v207, v207, v171
	v_cvt_pk_bf16_f32 v165, v170, v171
	v_exp_f32_e32 v172, v172
	v_exp_f32_e32 v173, v173
	v_mfma_f32_32x32x16_bf16 v[80:95], v[230:233], v[176:179], v[80:95]
	v_add_f32_e32 v207, v207, v172
	v_add_f32_e32 v207, v207, v173
	v_cvt_pk_bf16_f32 v166, v172, v173
	v_exp_f32_e32 v174, v174
	v_mfma_f32_32x32x16_bf16 v[48:63], v[240:243], v[176:179], v[48:63]
	v_exp_f32_e32 v175, v175
	v_add_f32_e32 v207, v207, v174
	v_add_f32_e32 v207, v207, v175
	v_cvt_pk_bf16_f32 v167, v174, v175
	v_mfma_f32_32x32x16_bf16 v[16:31], v[192:195], v[176:179], v[16:31]
	v_exp_f32_e32 v184, v184
	v_exp_f32_e32 v185, v185
	v_add_f32_e32 v206, v206, v184
	v_add_f32_e32 v206, v206, v185
	s_waitcnt lgkmcnt(3)
	v_mfma_f32_32x32x16_bf16 v[112:127], v[210:213], v[164:167], v[112:127]
	v_cvt_pk_bf16_f32 v180, v184, v185
	v_exp_f32_e32 v186, v186
	v_exp_f32_e32 v187, v187
	v_add_f32_e32 v206, v206, v186
	s_waitcnt lgkmcnt(2)
	v_mfma_f32_32x32x16_bf16 v[64:79], v[214:217], v[164:167], v[64:79]
	v_add_f32_e32 v206, v206, v187
	v_cvt_pk_bf16_f32 v181, v186, v187
	v_exp_f32_e32 v188, v188
	v_exp_f32_e32 v189, v189
	s_waitcnt lgkmcnt(1)
	v_mfma_f32_32x32x16_bf16 v[32:47], v[218:221], v[164:167], v[32:47]
	v_add_f32_e32 v206, v206, v188
	v_add_f32_e32 v206, v206, v189
	v_cvt_pk_bf16_f32 v182, v188, v189
	v_exp_f32_e32 v190, v190
	s_waitcnt lgkmcnt(0)
	v_mfma_f32_32x32x16_bf16 v[0:15], v[222:225], v[164:167], v[0:15]
	v_exp_f32_e32 v191, v191
	v_add_f32_e32 v206, v206, v190
	v_add_f32_e32 v206, v206, v191
	v_cvt_pk_bf16_f32 v183, v190, v191

; #define MFMA32(a, b, c) __builtin_amdgcn_mfma_f32_32x32x16_bf16((a), (b), (c), 0, 0, 0)
; DI void attn_item(const Params& p, char* lds, int l, int bh, int jt, float lam, float outscale) {
;     ...
;       for (int s = 0; s < 2; ++s) {
; #pragma unroll
;         for (int d = 0; d < 4; ++d) {
;           const bf16x8 vf = VFRAG(1, d, s);
;           O0[d] = MFMA32(vf, pc0[s], O0[d]);
;           O1[d] = MFMA32(vf, pc1[s], O1[d]);
;         }
;       }
.Lattn_exit:
	s_add_i32 vcc_lo, s24, -1
	s_cmp_lt_i32 s25, vcc_lo
	s_cbranch_scc1 .LBB0_722
	v_mfma_f32_32x32x16_bf16 v[96:111], v[210:213], v[180:183], v[96:111]
	v_mfma_f32_32x32x16_bf16 v[80:95], v[214:217], v[180:183], v[80:95]
	v_mfma_f32_32x32x16_bf16 v[48:63], v[218:221], v[180:183], v[48:63]
	v_mfma_f32_32x32x16_bf16 v[16:31], v[222:225], v[180:183], v[16:31]
	s_branch .LBB0_722
.Lattn_a_idle:
	s_add_i32 vcc_lo, s25, 1
	s_cmp_lg_u32 s35, vcc_lo
	s_cbranch_scc1 .Lattn_idle_nd
	v_mfma_f32_32x32x16_bf16 v[96:111], v[210:213], v[180:183], v[96:111]
	v_mfma_f32_32x32x16_bf16 v[80:95], v[214:217], v[180:183], v[80:95]
	v_mfma_f32_32x32x16_bf16 v[48:63], v[218:221], v[180:183], v[48:63]
	v_mfma_f32_32x32x16_bf16 v[16:31], v[222:225], v[180:183], v[16:31]
